# v101 plus attention K-fragment prefetch across the tile barrier and MFMA-first tile head
# speedup vs baseline: 1.0036x; 1.0036x over previous
.Latt_mla_dmaend:
	v_mfma_f32_32x32x16_bf16 v[64:79], v[120:123], v[138:141], v[64:79]
	ds_read_b128 v[120:123], v217 offset:224
	v_mfma_f32_32x32x16_bf16 v[64:79], v[124:127], v[142:145], v[64:79]
	ds_read_b128 v[124:127], v217 offset:256
	v_mfma_f32_32x32x16_bf16 v[64:79], v[250:253], v[146:149], v[64:79]
	ds_read_b128 v[250:253], v217 offset:288
	s_waitcnt lgkmcnt(3)
	v_mfma_f32_32x32x16_bf16 v[64:79], v[112:115], v[150:153], v[64:79]
	ds_read_b128 v[112:115], v217 offset:320
	v_mfma_f32_32x32x16_bf16 v[64:79], v[116:119], v[154:157], v[64:79]
	ds_read_b128 v[116:119], v217 offset:352
	s_waitcnt lgkmcnt(3)
	v_mfma_f32_32x32x16_bf16 v[64:79], v[120:123], v[158:161], v[64:79]
	ds_read_b128 v[120:123], v217 offset:12800
	v_mfma_f32_32x32x16_bf16 v[64:79], v[124:127], v[162:165], v[64:79]
	ds_read_b128 v[124:127], v217 offset:12832
	s_waitcnt lgkmcnt(3)
	v_mfma_f32_32x32x16_bf16 v[64:79], v[250:253], v[166:169], v[64:79]
	ds_read_b128 v[250:253], v217 offset:12864
	v_mfma_f32_32x32x16_bf16 v[64:79], v[112:115], v[170:173], v[64:79]
	ds_read_b128 v[112:115], v217 offset:12896
	s_waitcnt lgkmcnt(3)
	v_mfma_f32_32x32x16_bf16 v[64:79], v[116:119], v[174:177], v[64:79]
	ds_read_b128 v[116:119], v217 offset:12928
	v_mfma_f32_32x32x16_bf16 v[80:95], v[120:123], v[130:133], v[96:111]
	ds_read_b128 v[120:123], v217 offset:12960
	s_waitcnt lgkmcnt(3)
	v_mfma_f32_32x32x16_bf16 v[80:95], v[124:127], v[134:137], v[80:95]
	ds_read_b128 v[124:127], v217 offset:12992
	v_mfma_f32_32x32x16_bf16 v[80:95], v[250:253], v[138:141], v[80:95]
	ds_read_b128 v[250:253], v217 offset:13024
	s_waitcnt lgkmcnt(3)
	v_mfma_f32_32x32x16_bf16 v[80:95], v[112:115], v[142:145], v[80:95]
	ds_read_b128 v[112:115], v217 offset:13056
	v_mfma_f32_32x32x16_bf16 v[80:95], v[116:119], v[146:149], v[80:95]
	ds_read_b128 v[116:119], v217 offset:13088
	v_max3_f32 v211, v64, v65, v66
	s_waitcnt lgkmcnt(3)
	v_mfma_f32_32x32x16_bf16 v[80:95], v[120:123], v[150:153], v[80:95]
	ds_read_b128 v[120:123], v217 offset:13120
	v_max3_f32 v213, v67, v68, v69
	v_mfma_f32_32x32x16_bf16 v[80:95], v[124:127], v[154:157], v[80:95]
	ds_read_b128 v[124:127], v217 offset:13152
	v_max3_f32 v211, v211, v70, v71
	s_waitcnt lgkmcnt(3)
	v_mfma_f32_32x32x16_bf16 v[80:95], v[250:253], v[158:161], v[80:95]
	v_max3_f32 v213, v213, v72, v73
	v_mfma_f32_32x32x16_bf16 v[80:95], v[112:115], v[162:165], v[80:95]
	v_max3_f32 v211, v211, v74, v75
	s_waitcnt lgkmcnt(1)
	v_mfma_f32_32x32x16_bf16 v[80:95], v[116:119], v[166:169], v[80:95]
	v_max3_f32 v213, v213, v76, v77
	v_mfma_f32_32x32x16_bf16 v[80:95], v[120:123], v[170:173], v[80:95]
	v_max3_f32 v211, v211, v78, v79
	s_waitcnt lgkmcnt(0)
	v_mfma_f32_32x32x16_bf16 v[80:95], v[124:127], v[174:177], v[80:95]
	ds_read_b128 v[112:115], v219 offset:0
	ds_read_b128 v[116:119], v219 offset:4608
	ds_read_b128 v[120:123], v219 offset:9216
	s_add_i32 s30, s52, 1
	s_cmp_lg_u32 s52, 2
	s_cselect_b32 s57, s30, 0
	s_add_i32 s49, s49, 64
	s_add_i32 s51, s51, 64
	s_mov_b32 s56, s53
	s_mov_b32 s53, s52
	s_mov_b32 s52, s57
	s_nop 0
	v_max3_f32 v215, v80, v81, v82
	v_max3_f32 v209, v83, v84, v85
	v_max3_f32 v215, v215, v86, v87
	v_max3_f32 v209, v209, v88, v89
	v_max3_f32 v215, v215, v90, v91
	v_max3_f32 v209, v209, v92, v93
	v_max3_f32 v215, v215, v94, v95
	v_max3_f32 v209, v209, v211, v213
	v_max_f32_e32 v209, v209, v215
	v_cmp_lt_f32_e32 vcc, s58, v209
	s_cbranch_vccnz .Latt_mla_rare
.Latt_mla_norescale:
	v_exp_f32_e32 v64, v64
	v_exp_f32_e32 v65, v65
	v_exp_f32_e32 v66, v66
	v_exp_f32_e32 v67, v67
	v_exp_f32_e32 v68, v68
	v_exp_f32_e32 v69, v69
	v_exp_f32_e32 v70, v70
	v_exp_f32_e32 v71, v71
	v_cvt_pk_bf16_f32 v124, v64, v65
	v_cvt_pk_bf16_f32 v125, v66, v67
	v_cvt_pk_bf16_f32 v126, v68, v69
	v_cvt_pk_bf16_f32 v127, v70, v71
	s_waitcnt lgkmcnt(1)
	s_nop 0
	v_mfma_f32_32x32x16_bf16 v[48:63], v[112:115], v[124:127], v[48:63]
	ds_read_b128 v[112:115], v219 offset:13824
	v_exp_f32_e32 v72, v72
	v_exp_f32_e32 v73, v73
	v_exp_f32_e32 v74, v74
	v_exp_f32_e32 v75, v75
	v_mfma_f32_32x32x16_bf16 v[32:47], v[116:119], v[124:127], v[32:47]
	ds_read_b128 v[116:119], v219 offset:32
	v_cvt_pk_bf16_f32 v250, v72, v73
	v_exp_f32_e32 v76, v76
	v_exp_f32_e32 v77, v77
	v_cvt_pk_bf16_f32 v251, v74, v75
	s_waitcnt lgkmcnt(1)
	v_mfma_f32_32x32x16_bf16 v[16:31], v[120:123], v[124:127], v[16:31]
	ds_read_b128 v[120:123], v219 offset:4640
	v_exp_f32_e32 v78, v78
	v_exp_f32_e32 v79, v79
	v_cvt_pk_bf16_f32 v252, v76, v77
	v_cvt_pk_bf16_f32 v253, v78, v79
	v_mfma_f32_32x32x16_bf16 v[0:15], v[112:115], v[124:127], v[0:15]
	ds_read_b128 v[112:115], v219 offset:9248
	v_add_f32_e32 v209, v64, v68
	v_add_f32_e32 v211, v65, v69
	v_add_f32_e32 v213, v66, v70
	v_add_f32_e32 v215, v67, v71
	s_waitcnt lgkmcnt(1)
	v_mfma_f32_32x32x16_bf16 v[48:63], v[116:119], v[250:253], v[48:63]
	ds_read_b128 v[64:67], v219 offset:13856
	ds_read_b128 v[68:71], v219 offset:64
	v_exp_f32_e32 v80, v80
	v_exp_f32_e32 v81, v81
	v_exp_f32_e32 v82, v82
	v_exp_f32_e32 v83, v83
	v_cvt_pk_bf16_f32 v124, v80, v81
	v_mfma_f32_32x32x16_bf16 v[32:47], v[120:123], v[250:253], v[32:47]
	ds_read_b128 v[116:119], v219 offset:4672
	ds_read_b128 v[120:123], v219 offset:9280
	v_exp_f32_e32 v84, v84
	v_exp_f32_e32 v85, v85
	v_cvt_pk_bf16_f32 v125, v82, v83
	v_exp_f32_e32 v86, v86
	v_exp_f32_e32 v87, v87
	s_waitcnt lgkmcnt(3)
	v_mfma_f32_32x32x16_bf16 v[16:31], v[112:115], v[250:253], v[16:31]
	ds_read_b128 v[112:115], v219 offset:13888
	v_cvt_pk_bf16_f32 v126, v84, v85
	v_cvt_pk_bf16_f32 v127, v86, v87
	v_add_f32_e32 v209, v209, v72
	v_add_f32_e32 v211, v211, v73
	v_add_f32_e32 v213, v213, v74
	v_mfma_f32_32x32x16_bf16 v[0:15], v[64:67], v[250:253], v[0:15]
	ds_read_b128 v[64:67], v219 offset:96
	v_add_f32_e32 v215, v215, v75
	v_add_f32_e32 v209, v209, v76
	v_add_f32_e32 v211, v211, v77
	v_add_f32_e32 v213, v213, v78
	v_add_f32_e32 v215, v215, v79
	s_waitcnt lgkmcnt(3)
	v_mfma_f32_32x32x16_bf16 v[48:63], v[68:71], v[124:127], v[48:63]
	ds_read_b128 v[72:75], v219 offset:4704
	ds_read_b128 v[76:79], v219 offset:9312
	v_exp_f32_e32 v88, v88
	v_exp_f32_e32 v89, v89
	v_exp_f32_e32 v90, v90
	v_exp_f32_e32 v91, v91
	v_cvt_pk_bf16_f32 v250, v88, v89
	v_mfma_f32_32x32x16_bf16 v[32:47], v[116:119], v[124:127], v[32:47]
	ds_read_b128 v[68:71], v219 offset:13920
	v_exp_f32_e32 v92, v92
	v_exp_f32_e32 v93, v93
	v_cvt_pk_bf16_f32 v251, v90, v91
	v_exp_f32_e32 v94, v94
	v_exp_f32_e32 v95, v95
	s_waitcnt lgkmcnt(4)
	v_mfma_f32_32x32x16_bf16 v[16:31], v[120:123], v[124:127], v[16:31]
	v_cvt_pk_bf16_f32 v252, v92, v93
	v_cvt_pk_bf16_f32 v253, v94, v95
	v_add_f32_e32 v209, v209, v80
	v_add_f32_e32 v211, v211, v81
	v_add_f32_e32 v213, v213, v82
	v_mfma_f32_32x32x16_bf16 v[0:15], v[112:115], v[124:127], v[0:15]
	v_add_f32_e32 v215, v215, v83
	v_add_f32_e32 v209, v209, v84
	v_add_f32_e32 v211, v211, v85
	v_add_f32_e32 v213, v213, v86
	v_add_f32_e32 v215, v215, v87
	s_waitcnt lgkmcnt(2)
	v_mfma_f32_32x32x16_bf16 v[48:63], v[64:67], v[250:253], v[48:63]
	s_mul_i32 s30, s56, 0x6400
	v_add_u32_e32 v217, s30, v246
	ds_read_b128 v[112:115], v217 offset:0
	v_add_f32_e32 v209, v209, v88
	v_add_f32_e32 v211, v211, v89
	v_mfma_f32_32x32x16_bf16 v[32:47], v[72:75], v[250:253], v[32:47]
	ds_read_b128 v[116:119], v217 offset:32
	v_add_f32_e32 v213, v213, v90
	v_add_f32_e32 v215, v215, v91
	s_waitcnt lgkmcnt(2)
	v_mfma_f32_32x32x16_bf16 v[16:31], v[76:79], v[250:253], v[16:31]
	ds_read_b128 v[120:123], v217 offset:64
	v_add_f32_e32 v209, v209, v92
	v_add_f32_e32 v211, v211, v93
	v_mfma_f32_32x32x16_bf16 v[0:15], v[68:71], v[250:253], v[0:15]
	ds_read_b128 v[124:127], v217 offset:96
	v_add_f32_e32 v213, v213, v94
	v_add_f32_e32 v215, v215, v95
	ds_read_b128 v[250:253], v217 offset:128
	v_add_f32_e32 v209, v209, v211
	v_add_f32_e32 v213, v213, v215
	v_add_f32_e32 v209, v209, v213
	v_add_f32_e32 v205, v205, v209
.Latt_mla_skip:
	s_waitcnt vmcnt(0)
	s_add_i32 s55, s55, 1
	s_mul_i32 s30, s56, 0x4800
	v_add_u32_e32 v219, s30, v247
	s_cmp_eq_u32 s20, s55
	s_waitcnt lgkmcnt(0)
	s_barrier
	s_cbranch_scc0 .LBB0_178
	s_branch .LBB0_153
